# first unit's K-tile-0 staging loads issued before the row-scale table loop in the G3, G1H and G1S phases (latency overlaps the table's round trips)
# speedup vs baseline: 1.0058x; 1.0058x over previous
.LBB0_141:
	s_andn2_b64 vcc, exec, s[4:5]
	s_cbranch_vccnz .LBB0_352
	v_readlane_b32 s2, v254, 36
	s_add_u32 s30, s2, s16
	v_readlane_b32 s2, v254, 39
	v_ashrrev_i32_e32 v2, 8, v170
	s_addc_u32 s31, s2, s17
	v_cmp_gt_i32_e32 vcc, 8, v2
	s_and_saveexec_b64 s[38:39], vcc
	v_readlane_b32 s0, v254, 40
	s_mov_b64 s[80:81], 0x200
	v_readlane_b32 s1, v254, 41
	s_cmp_gt_i32 s22, 63
	s_cselect_b64 s[98:99], -1, 0
	s_and_b64 s[98:99], s[98:99], s[0:1]
	s_and_b64 vcc, exec, s[98:99]
	s_cbranch_vccnz .Lhoist_g3a_skip
	v_readlane_b32 s84, v254, 31
	v_readlane_b32 s82, v254, 37
	v_readlane_b32 s83, v254, 38
	s_mul_i32 s84, s84, 0xb00000
	s_add_u32 s84, s82, s84
	s_addc_u32 s85, s83, 0
	s_add_u32 s84, s84, 0x2100000
	s_addc_u32 s85, s85, 0
	s_mov_b32 s76, s72
	s_ashr_i32 s77, s72, 31
	s_lshl_b64 s[76:77], s[76:77], 19
	s_add_u32 s84, s84, s76
	s_addc_u32 s85, s85, s77
	s_mov_b32 s76, s22
	s_ashr_i32 s77, s22, 31
	s_lshl_b64 s[76:77], s[76:77], 19
	s_add_u32 s82, s48, s76
	s_addc_u32 s83, s49, s77
	s_ashr_i32 s86, s29, 6
	s_lshl_b32 s86, s86, 10
	s_add_i32 m0, s86, 0x10000
	s_nop 0
	global_load_lds_dwordx4 v164, s[84:85]
	s_add_i32 m0, s86, 0x12000
	s_nop 0
	global_load_lds_dwordx4 v174, s[84:85]
	s_add_u32 s76, s84, 0x40000
	s_addc_u32 s77, s85, 0
	s_add_i32 m0, s86, 0x14000
	s_nop 0
	global_load_lds_dwordx4 v164, s[76:77]
	s_add_i32 m0, s86, 0x16000
	s_nop 0
	global_load_lds_dwordx4 v174, s[76:77]
	s_mov_b32 m0, s86
	s_nop 0
	global_load_lds_dwordx4 v162, s[82:83]
	s_add_i32 m0, s86, 0x2000
	s_nop 0
	global_load_lds_dwordx4 v172, s[82:83]
	s_add_u32 s76, s82, 0x40000
	s_addc_u32 s77, s83, 0
	s_add_i32 m0, s86, 0x4000
	s_nop 0
	global_load_lds_dwordx4 v162, s[76:77]
	s_add_i32 m0, s86, 0x6000
	s_nop 0
	global_load_lds_dwordx4 v172, s[76:77]
.Lhoist_g3a_skip:
	s_cbranch_execz .LBB0_229
	s_lshr_b32 s21, s10, 3
	s_ashr_i32 s91, s90, 31
	s_ashr_i32 s59, s94, 31
	s_and_b32 s23, s10, 4
	s_add_i32 s26, s21, 1
	s_cmpk_gt_i32 s94, 0x7f
	s_cselect_b64 s[40:41], -1, 0
	s_cmpk_gt_u32 s94, 0x97
	s_cselect_b64 s[42:43], -1, 0
	s_cmpk_gt_u32 s94, 0xc3
	s_cselect_b64 s[44:45], -1, 0
	s_cmpk_gt_u32 s94, 0xf7
	s_cselect_b64 s[50:51], -1, 0
	s_cmpk_lt_u32 s94, 0xcc
	s_cselect_b64 s[52:53], -1, 0
	s_cmpk_lt_u32 s94, 0xf4
	s_movk_i32 s2, 0xffd0
	s_cselect_b32 s2, s2, 0xffffffa4
	s_add_i32 s4, s2, s94
	s_add_i32 s16, s4, 0x400
	s_and_b32 s4, s4, 7
	v_mov_b32_e32 v0, s23
	v_sub_co_u32_e32 v3, vcc, s4, v0
	s_nop 0
	v_readfirstlane_b32 s5, v3
	s_mul_i32 s27, s26, s23
	s_mul_i32 s5, s5, s21
	s_lshr_b32 s62, s16, 3
	s_add_i32 s63, s27, s5
	s_mul_i32 s64, s26, s4
	s_add_i32 s4, s94, 0x134
	s_cmp_lt_i32 s4, s10
	s_cselect_b64 s[54:55], -1, 0
	s_and_b32 s6, s4, 7
	v_sub_co_u32_e64 v3, s[4:5], s6, v0
	s_nop 0
	v_readfirstlane_b32 s7, v3
	s_mul_i32 s7, s7, s21
	s_add_i32 s65, s27, s7
	s_mul_i32 s66, s26, s6
	s_add_i32 s6, s94, 0xffffff52
	s_cmp_lt_u32 s6, 0xffffffea
	s_mov_b32 s11, s17
	s_cselect_b32 s71, 0x41, 64
	s_add_i32 s6, s94, 0xffffff80
	v_mov_b64_e32 v[4:5], s[10:11]
	s_lshr_b32 s6, s6, 3
	v_cmp_ge_u64_e64 s[2:3], s[16:17], v[4:5]
	s_add_i32 s16, s6, 2
	s_lshl_b64 s[6:7], s[16:17], 8
	s_add_u32 s6, s6, s94
	s_addc_u32 s9, s7, 0
	s_or_b32 s8, s6, 0xf8
	v_cmp_ge_u64_e64 s[6:7], s[8:9], v[4:5]
	s_lshr_b32 s74, s8, 3
	v_sub_co_u32_e64 v0, s[8:9], s70, v0
	s_nop 0
	v_readfirstlane_b32 s16, v0
	s_mul_i32 s16, s16, s21
	s_add_i32 s67, s27, s16
	s_and_b64 s[60:61], vcc, exec
	s_cselect_b32 s16, s64, s63
	s_add_i32 s16, s16, s62
	s_and_b64 s[4:5], s[4:5], exec
	s_cselect_b32 s73, s66, s65
	s_add_i32 s73, s73, 63
	s_mov_b64 s[78:79], s[68:69]
	s_mul_i32 s68, s26, s70
	v_and_b32_e32 v0, 0xff, v170
	s_and_b64 s[4:5], s[8:9], exec
	s_cselect_b32 s4, s68, s67
	v_lshlrev_b32_e32 v8, 2, v0
	s_mov_b32 s58, s94
	s_add_i32 s74, s74, s4
	v_lshl_or_b32 v8, v2, 10, v8
	v_readlane_b32 s4, v254, 19
	v_ashrrev_i32_e32 v3, 31, v2
	s_mov_b32 s95, s17
	v_add_u32_e32 v12, s4, v8
	v_mov_b64_e32 v[8:9], s[58:59]
	v_lshlrev_b64 v[6:7], 8, v[2:3]
	v_mad_i64_i32 v[8:9], s[4:5], s90, v2, v[8:9]
	s_mov_b64 s[68:69], s[78:79]
	v_lshl_add_u64 v[4:5], v[6:7], 0, s[94:95]
	v_lshl_add_u64 v[6:7], v[6:7], 0, s[58:59]
	s_lshl_b64 s[4:5], s[90:91], 1
	s_mov_b64 s[8:9], 0
	s_xor_b64 s[6:7], s[6:7], -1
	s_branch .LBB0_148

.LBB0_241:
	v_writelane_b32 v254, s92, 44
	v_writelane_b32 v255, s68, 25
	s_waitcnt vmcnt(0)
	v_mov_b32_e32 v165, v1
	v_writelane_b32 v254, s93, 45
	v_mov_b32_e32 v175, v1
	v_readlane_b32 s2, v254, 31
	s_mul_i32 s2, s2, 0xb00000
	v_readlane_b32 s4, v254, 37
	v_readlane_b32 s5, v254, 38
	s_add_u32 s2, s4, s2
	s_addc_u32 s3, s5, 0
	s_add_u32 s6, s2, 0x2100000
	s_addc_u32 s7, s3, 0
	s_ashr_i32 s23, s22, 31
	s_lshl_b64 s[2:3], s[22:23], 19
	s_add_u32 s8, s48, s2
	s_addc_u32 s9, s49, s3
	s_ashr_i32 s73, s72, 31
	s_lshl_b64 s[2:3], s[72:73], 19
	s_add_u32 s74, s6, s2
	s_addc_u32 s75, s7, s3
	s_ashr_i32 s2, s29, 6
	s_lshl_b32 s20, s2, 10
	s_add_i32 s21, s20, 0
	s_add_i32 m0, s21, 0x10000
	s_ashr_i32 s3, s29, 8
	s_add_i32 m0, s21, 0x12000
	s_add_u32 s4, s74, 0x40000
	s_addc_u32 s5, s75, 0
	s_add_i32 m0, s21, 0x14000
	s_add_i32 s23, s21, 0x2000
	s_add_i32 m0, s21, 0x16000
	v_mov_b32_e32 v163, v1
	s_mov_b32 m0, s21
	s_add_u32 s4, s8, 0x40000
	s_mov_b32 m0, s23
	s_addc_u32 s5, s9, 0
	s_add_i32 s26, s21, 0x4000
	s_mov_b32 m0, s26
	s_add_i32 s27, s21, 0x6000
	s_mov_b32 m0, s27
	v_mov_b32_e32 v173, v1
	s_cmp_gt_i32 s22, 63
	s_cselect_b64 s[98:99], -1, 0
	s_and_b64 s[98:99], s[98:99], s[0:1]
	s_and_b64 vcc, exec, s[98:99]
	s_cbranch_vccz .Lhoist_g3b_skip
	v_readlane_b32 s84, v254, 31
	v_readlane_b32 s82, v254, 37
	v_readlane_b32 s83, v254, 38
	s_mul_i32 s84, s84, 0xb00000
	s_add_u32 s84, s82, s84
	s_addc_u32 s85, s83, 0
	s_add_u32 s84, s84, 0x2100000
	s_addc_u32 s85, s85, 0
	s_mov_b32 s76, s72
	s_ashr_i32 s77, s72, 31
	s_lshl_b64 s[76:77], s[76:77], 19
	s_add_u32 s84, s84, s76
	s_addc_u32 s85, s85, s77
	s_mov_b32 s76, s22
	s_ashr_i32 s77, s22, 31
	s_lshl_b64 s[76:77], s[76:77], 19
	s_add_u32 s82, s48, s76
	s_addc_u32 s83, s49, s77
	s_ashr_i32 s86, s29, 6
	s_lshl_b32 s86, s86, 10
	s_add_i32 m0, s86, 0x10000
	s_nop 0
	global_load_lds_dwordx4 v164, s[84:85]
	s_add_i32 m0, s86, 0x12000
	s_nop 0
	global_load_lds_dwordx4 v174, s[84:85]
	s_add_u32 s76, s84, 0x40000
	s_addc_u32 s77, s85, 0
	s_add_i32 m0, s86, 0x14000
	s_nop 0
	global_load_lds_dwordx4 v164, s[76:77]
	s_add_i32 m0, s86, 0x16000
	s_nop 0
	global_load_lds_dwordx4 v174, s[76:77]
	s_mov_b32 m0, s86
	s_nop 0
	global_load_lds_dwordx4 v162, s[82:83]
	s_add_i32 m0, s86, 0x2000
	s_nop 0
	global_load_lds_dwordx4 v172, s[82:83]
	s_add_u32 s76, s82, 0x40000
	s_addc_u32 s77, s83, 0
	s_add_i32 m0, s86, 0x4000
	s_nop 0
	global_load_lds_dwordx4 v162, s[76:77]
	s_add_i32 m0, s86, 0x6000
	s_nop 0
	global_load_lds_dwordx4 v172, s[76:77]
.Lhoist_g3b_skip:
	s_cmp_eq_u32 s3, 1
	s_mov_b32 s64, s90
	v_writelane_b32 v255, s69, 26
	v_lshl_add_u64 v[8:9], s[74:75], 0, v[164:165]
	v_lshl_add_u64 v[6:7], s[74:75], 0, v[174:175]
	v_lshl_add_u64 v[2:3], s[8:9], 0, v[162:163]
	s_cselect_b64 s[50:51], -1, 0
	s_cmp_lg_u32 s3, 1
	v_lshl_add_u64 v[4:5], s[8:9], 0, v[172:173]
	s_cbranch_scc1 .LBB0_243
	s_barrier

.LBB0_487:
	s_andn2_b64 vcc, exec, s[10:11]
	s_cbranch_vccnz .LBB0_614
	v_ashrrev_i32_e32 v2, 31, v170
	v_lshrrev_b32_e32 v2, 26, v2
	v_add_u32_e32 v2, v170, v2
	v_ashrrev_i32_e32 v10, 6, v2
	v_bfe_i32 v2, v170, 27, 1
	v_lshlrev_b32_e32 v0, 4, v170
	v_lshrrev_b32_e32 v2, 22, v2
	v_add_u32_e32 v2, v0, v2
	v_and_b32_e32 v2, 0xfffffc00, v2
	v_sub_u32_e32 v2, v0, v2
	v_lshrrev_b32_e32 v3, 4, v2
	v_bitop3_b32 v2, v3, v2, 32 bitop3:0x6c
	v_ashrrev_i32_e32 v4, 31, v2
	v_lshrrev_b32_e32 v4, 26, v4
	v_add_u32_e32 v4, v2, v4
	v_lshlrev_b32_e32 v3, 3, v10
	v_ashrrev_i32_e32 v11, 6, v4
	v_and_b32_e32 v4, 0xc0, v4
	v_and_b32_e32 v3, -16, v3
	v_sub_u32_e32 v2, v2, v4
	v_add_u32_e32 v3, v11, v3
	v_ashrrev_i16_sdwa v2, v209, sext(v2) dst_sel:DWORD dst_unused:UNUSED_PAD src0_sel:DWORD src1_sel:BYTE_0
	v_lshlrev_b32_e32 v5, 5, v10
	v_bfe_i32 v12, v2, 0, 16
	v_lshlrev_b32_e32 v2, 1, v3
	v_lshrrev_b32_e32 v4, 2, v3
	v_and_b32_e32 v6, 3, v11
	s_mov_b32 s58, 0x1fffe0
	v_and_b32_e32 v5, 32, v5
	v_and_b32_e32 v2, 24, v2
	v_and_b32_e32 v4, 4, v4
	v_and_or_b32 v6, v3, s58, v6
	v_or3_b32 v2, v6, v4, v2
	v_add_lshl_u32 v4, v5, v12, 1
	v_add_u32_e32 v0, 0x2000, v0
	v_lshl_add_u32 v152, v2, 11, v4
	v_ashrrev_i32_e32 v2, 31, v0
	v_lshrrev_b32_e32 v2, 22, v2
	v_add_u32_e32 v2, v0, v2
	v_ashrrev_i32_e32 v13, 10, v2
	v_mul_i32_i24_e32 v2, 0x400, v13
	v_sub_u32_e32 v0, v0, v2
	v_lshrrev_b32_e32 v2, 4, v0
	v_bitop3_b32 v0, v2, v0, 32 bitop3:0x6c
	v_lshl_add_u32 v150, v3, 11, v4
	v_ashrrev_i32_e32 v3, 31, v0
	v_lshrrev_b32_e32 v3, 26, v3
	v_lshlrev_b32_e32 v2, 3, v13
	v_add_u32_e32 v3, v0, v3
	v_and_b32_e32 v2, -16, v2
	v_ashrrev_i32_e32 v14, 6, v3
	v_add_u32_e32 v2, v14, v2
	v_and_b32_e32 v5, 3, v14
	v_and_or_b32 v5, v2, s58, v5
	v_and_b32_e32 v3, 0xc0, v3
	v_sub_u32_e32 v0, v0, v3
	v_ashrrev_i16_sdwa v0, v209, sext(v0) dst_sel:DWORD dst_unused:UNUSED_PAD src0_sel:DWORD src1_sel:BYTE_0
	v_lshlrev_b32_e32 v4, 5, v13
	v_bfe_i32 v15, v0, 0, 16
	v_lshlrev_b32_e32 v0, 1, v2
	v_lshrrev_b32_e32 v3, 2, v2
	v_and_b32_e32 v4, 32, v4
	v_and_b32_e32 v0, 24, v0
	v_and_b32_e32 v3, 4, v3
	v_or3_b32 v0, v5, v3, v0
	v_add_lshl_u32 v3, v4, v15, 1
	v_lshl_add_u32 v156, v0, 11, v3
	v_lshl_add_u32 v154, v2, 11, v3
	s_ashr_i32 s58, s16, 6
	s_lshl_b32 s52, s58, 10
	v_readlane_b32 s60, v254, 37
	v_readlane_b32 s61, v254, 38
	s_mul_i32 s62, s24, 0x300000
	s_add_u32 s62, s60, s62
	s_addc_u32 s63, s61, 0
	s_add_u32 s62, s62, 0xf00000
	s_addc_u32 s63, s63, 0
	s_mov_b32 s66, s2
	s_ashr_i32 s67, s2, 31
	s_lshl_b64 s[66:67], s[66:67], 19
	s_add_u32 s46, s62, s66
	s_addc_u32 s47, s63, s67
	s_mov_b32 s66, s42
	s_ashr_i32 s67, s42, 31
	s_lshl_b64 s[66:67], s[66:67], 19
	s_add_u32 s44, s60, 0xab00000
	s_addc_u32 s45, s61, 0
	s_add_u32 s44, s44, s66
	s_addc_u32 s45, s45, s67
	s_add_i32 m0, s52, 0x10000
	s_nop 0
	global_load_lds_dwordx4 v152, s[46:47]
	s_add_i32 m0, s52, 0x12000
	s_nop 0
	global_load_lds_dwordx4 v156, s[46:47]
	s_add_u32 s66, s46, 0x40000
	s_addc_u32 s67, s47, 0
	s_add_i32 m0, s52, 0x14000
	s_nop 0
	global_load_lds_dwordx4 v152, s[66:67]
	s_add_i32 m0, s52, 0x16000
	s_nop 0
	global_load_lds_dwordx4 v156, s[66:67]
	s_mov_b32 m0, s52
	s_nop 0
	global_load_lds_dwordx4 v150, s[44:45]
	s_add_i32 m0, s52, 0x2000
	s_nop 0
	global_load_lds_dwordx4 v154, s[44:45]
	s_add_u32 s66, s44, 0x40000
	s_addc_u32 s67, s45, 0
	s_add_i32 m0, s52, 0x4000
	s_nop 0
	global_load_lds_dwordx4 v150, s[66:67]
	s_add_i32 m0, s52, 0x6000
	s_nop 0
	global_load_lds_dwordx4 v154, s[66:67]
	v_ashrrev_i32_e32 v2, 8, v170
	s_ashr_i32 s95, s94, 31
	v_cmp_gt_i32_e32 vcc, 8, v2
	s_and_saveexec_b64 s[10:11], vcc
	s_cbranch_execz .LBB0_499
	v_and_b32_e32 v0, 0xff, v170
	s_waitcnt lgkmcnt(0)
	v_lshlrev_b32_e32 v3, 2, v0
	v_add_u32_e32 v6, -2, v2
	v_lshl_or_b32 v3, v2, 10, v3
	v_readlane_b32 s3, v254, 19
	v_mul_lo_u32 v2, s90, v2
	s_ashr_i32 s91, s90, 31
	v_add_u32_e32 v8, s3, v3
	v_add_u32_e32 v7, s94, v2
	v_mov_b64_e32 v[2:3], s[94:95]
	s_lshl_b32 s3, s90, 1
	v_mad_i64_i32 v[2:3], s[20:21], v6, s90, v[2:3]
	s_lshl_b64 s[22:23], s[90:91], 1
	s_mov_b64 s[30:31], 0
	s_branch .LBB0_492

.LBB0_499:
	s_or_b64 exec, exec, s[10:11]
	v_ashrrev_i32_e32 v2, 31, v170
	v_lshrrev_b32_e32 v2, 26, v2
	v_add_u32_e32 v2, v170, v2
	v_ashrrev_i32_e32 v10, 6, v2
	v_bfe_i32 v2, v170, 27, 1
	v_lshlrev_b32_e32 v0, 4, v170
	v_lshrrev_b32_e32 v2, 22, v2
	v_add_u32_e32 v2, v0, v2
	v_and_b32_e32 v2, 0xfffffc00, v2
	v_sub_u32_e32 v2, v0, v2
	s_waitcnt lgkmcnt(0)
	v_lshrrev_b32_e32 v3, 4, v2
	v_bitop3_b32 v2, v3, v2, 32 bitop3:0x6c
	v_ashrrev_i32_e32 v4, 31, v2
	v_lshrrev_b32_e32 v4, 26, v4
	v_add_u32_e32 v4, v2, v4
	v_lshlrev_b32_e32 v3, 3, v10
	v_ashrrev_i32_e32 v11, 6, v4
	v_and_b32_e32 v4, 0xc0, v4
	v_and_b32_e32 v3, -16, v3
	v_sub_u32_e32 v2, v2, v4
	v_add_u32_e32 v3, v11, v3
	v_ashrrev_i16_sdwa v2, v209, sext(v2) dst_sel:DWORD dst_unused:UNUSED_PAD src0_sel:DWORD src1_sel:BYTE_0
	v_lshlrev_b32_e32 v5, 5, v10
	v_bfe_i32 v12, v2, 0, 16
	v_lshlrev_b32_e32 v2, 1, v3
	v_lshrrev_b32_e32 v4, 2, v3
	v_and_b32_e32 v6, 3, v11
	s_mov_b32 s3, 0x1fffe0
	v_and_b32_e32 v5, 32, v5
	v_and_b32_e32 v2, 24, v2
	v_and_b32_e32 v4, 4, v4
	v_and_or_b32 v6, v3, s3, v6
	v_or3_b32 v2, v6, v4, v2
	v_add_lshl_u32 v4, v5, v12, 1
	v_add_u32_e32 v0, 0x2000, v0
	s_waitcnt vmcnt(0)
	v_lshl_add_u32 v152, v2, 11, v4
	v_ashrrev_i32_e32 v2, 31, v0
	v_lshrrev_b32_e32 v2, 22, v2
	v_add_u32_e32 v2, v0, v2
	v_ashrrev_i32_e32 v13, 10, v2
	v_mul_i32_i24_e32 v2, 0x400, v13
	v_sub_u32_e32 v0, v0, v2
	v_lshrrev_b32_e32 v2, 4, v0
	v_bitop3_b32 v0, v2, v0, 32 bitop3:0x6c
	v_lshl_add_u32 v150, v3, 11, v4
	v_ashrrev_i32_e32 v3, 31, v0
	v_lshrrev_b32_e32 v3, 26, v3
	s_ashr_i32 s8, s16, 6
	v_lshlrev_b32_e32 v2, 3, v13
	v_add_u32_e32 v3, v0, v3
	v_and_b32_e32 v2, -16, v2
	v_ashrrev_i32_e32 v14, 6, v3
	s_ashr_i32 s9, s16, 8
	s_lshl_b32 s12, s8, 10
	v_readlane_b32 s6, v254, 37
	v_add_u32_e32 v2, v14, v2
	v_and_b32_e32 v5, 3, v14
	v_readlane_b32 s7, v254, 38
	s_add_u32 s20, s6, 0xab00000
	v_and_or_b32 v5, v2, s3, v5
	s_addc_u32 s21, s7, 0
	s_mul_i32 s3, s24, 0x300000
	s_add_u32 s3, s6, s3
	s_addc_u32 s6, s7, 0
	s_add_u32 s26, s3, 0xf00000
	v_and_b32_e32 v3, 0xc0, v3
	s_addc_u32 s27, s6, 0
	s_ashr_i32 s43, s42, 31
	s_ashr_i32 s3, s2, 31
	v_sub_u32_e32 v0, v0, v3
	s_lshl_b64 s[6:7], s[42:43], 19
	s_lshl_b64 s[10:11], s[2:3], 19
	v_ashrrev_i16_sdwa v0, v209, sext(v0) dst_sel:DWORD dst_unused:UNUSED_PAD src0_sel:DWORD src1_sel:BYTE_0
	s_add_u32 s46, s26, s10
	v_lshlrev_b32_e32 v4, 5, v13
	v_bfe_i32 v15, v0, 0, 16
	v_lshlrev_b32_e32 v0, 1, v2
	v_lshrrev_b32_e32 v3, 2, v2
	s_addc_u32 s47, s27, s11
	s_add_i32 s52, s12, 0
	v_and_b32_e32 v4, 32, v4
	v_and_b32_e32 v0, 24, v0
	v_and_b32_e32 v3, 4, v3
	s_waitcnt vmcnt(0) lgkmcnt(0)
	s_barrier
	s_add_i32 m0, s52, 0x10000
	v_or3_b32 v0, v5, v3, v0
	v_add_lshl_u32 v3, v4, v15, 1
	s_add_i32 m0, s52, 0x12000
	v_lshl_add_u32 v156, v0, 11, v3
	s_add_u32 s10, s46, 0x40000
	s_addc_u32 s11, s47, 0
	s_add_i32 m0, s52, 0x14000
	v_lshl_add_u32 v154, v2, 11, v3
	s_add_i32 m0, s52, 0x16000
	s_add_u32 s44, s20, s6
	s_addc_u32 s45, s21, s7
	s_add_i32 s53, s52, 0x2000
	s_mov_b32 m0, s52
	s_add_u32 s6, s44, 0x40000
	s_mov_b32 m0, s53
	s_addc_u32 s7, s45, 0
	s_add_i32 s54, s52, 0x4000
	s_mov_b32 m0, s54
	s_add_i32 s55, s52, 0x6000
	s_mov_b32 m0, s55
	s_cmp_eq_u32 s9, 1
	v_mov_b32_e32 v153, v1
	v_mov_b32_e32 v157, v1
	v_mov_b32_e32 v151, v1
	v_mov_b32_e32 v155, v1
	s_cselect_b64 s[6:7], -1, 0
	v_lshl_add_u64 v[8:9], s[46:47], 0, v[152:153]
	v_lshl_add_u64 v[6:7], s[46:47], 0, v[156:157]
	v_lshl_add_u64 v[4:5], s[44:45], 0, v[150:151]
	v_lshl_add_u64 v[2:3], s[44:45], 0, v[154:155]
	s_and_b64 vcc, exec, s[6:7]
	s_cbranch_vccz .LBB0_501
	s_barrier

.LBB0_929:
	v_ashrrev_i32_e32 v0, 31, v170
	v_lshrrev_b32_e32 v0, 26, v0
	v_add_u32_e32 v0, v170, v0
	s_waitcnt vmcnt(0)
	v_ashrrev_i32_e32 v171, 6, v0
	v_bfe_i32 v0, v170, 27, 1
	v_lshlrev_b32_e32 v2, 4, v170
	v_lshrrev_b32_e32 v0, 22, v0
	v_add_u32_e32 v0, v2, v0
	v_and_b32_e32 v0, 0xfffffc00, v0
	v_sub_u32_e32 v0, v2, v0
	s_waitcnt lgkmcnt(0)
	v_lshrrev_b32_e32 v3, 4, v0
	v_bitop3_b32 v0, v3, v0, 32 bitop3:0x6c
	v_ashrrev_i32_e32 v4, 31, v0
	v_lshrrev_b32_e32 v4, 26, v4
	v_add_u32_e32 v4, v0, v4
	v_lshlrev_b32_e32 v3, 3, v171
	v_ashrrev_i32_e32 v173, 6, v4
	v_and_b32_e32 v4, 0xc0, v4
	v_and_b32_e32 v3, -16, v3
	v_sub_u32_e32 v0, v0, v4
	v_add_u32_e32 v3, v173, v3
	v_ashrrev_i16_sdwa v0, v209, sext(v0) dst_sel:DWORD dst_unused:UNUSED_PAD src0_sel:DWORD src1_sel:BYTE_0
	v_lshlrev_b32_e32 v5, 5, v171
	v_bfe_i32 v214, v0, 0, 16
	v_lshlrev_b32_e32 v0, 1, v3
	v_lshrrev_b32_e32 v4, 2, v3
	v_and_b32_e32 v6, 3, v173
	s_mov_b32 s8, 0x1fffe0
	v_and_b32_e32 v5, 32, v5
	v_and_b32_e32 v0, 24, v0
	v_and_b32_e32 v4, 4, v4
	v_and_or_b32 v6, v3, s8, v6
	v_or3_b32 v0, v6, v4, v0
	v_add_lshl_u32 v4, v5, v214, 1
	v_add_u32_e32 v2, 0x2000, v2
	v_lshl_add_u32 v150, v3, 11, v4
	v_ashrrev_i32_e32 v3, 31, v2
	v_lshrrev_b32_e32 v3, 22, v3
	v_add_u32_e32 v3, v2, v3
	v_ashrrev_i32_e32 v215, 10, v3
	v_mul_i32_i24_e32 v3, 0x400, v215
	v_sub_u32_e32 v2, v2, v3
	v_lshrrev_b32_e32 v3, 4, v2
	v_bitop3_b32 v2, v3, v2, 32 bitop3:0x6c
	v_lshl_add_u32 v0, v0, 11, v4
	v_ashrrev_i32_e32 v4, 31, v2
	v_lshrrev_b32_e32 v4, 26, v4
	v_add_u32_e32 v4, v2, v4
	v_lshlrev_b32_e32 v3, 3, v215
	v_ashrrev_i32_e32 v216, 6, v4
	v_and_b32_e32 v4, 0xc0, v4
	v_and_b32_e32 v3, -16, v3
	v_sub_u32_e32 v2, v2, v4
	v_add_u32_e32 v3, v216, v3
	v_ashrrev_i16_sdwa v2, v209, sext(v2) dst_sel:DWORD dst_unused:UNUSED_PAD src0_sel:DWORD src1_sel:BYTE_0
	v_lshlrev_b32_e32 v5, 5, v215
	v_bfe_i32 v217, v2, 0, 16
	v_lshlrev_b32_e32 v2, 1, v3
	v_lshrrev_b32_e32 v4, 2, v3
	v_and_b32_e32 v6, 3, v216
	v_and_b32_e32 v5, 32, v5
	v_and_b32_e32 v2, 24, v2
	v_and_b32_e32 v4, 4, v4
	v_and_or_b32 v6, v3, s8, v6
	v_or3_b32 v2, v6, v4, v2
	v_add_lshl_u32 v4, v5, v217, 1
	v_lshl_add_u32 v154, v2, 11, v4
	v_lshrrev_b32_e32 v2, 1, v170
	v_lshl_add_u32 v152, v3, 11, v4
	v_and_b32_e32 v219, 15, v170
	v_and_b32_e32 v218, 24, v2
	v_lshlrev_b32_e32 v3, 2, v170
	v_lshlrev_b32_e32 v156, 1, v218
	v_lshlrev_b32_e32 v2, 6, v219
	v_and_b32_e32 v3, 32, v3
	s_andn2_b64 vcc, exec, s[6:7]
	v_bitop3_b32 v220, v156, v3, v2 bitop3:0x36
	s_cbranch_vccnz .LBB0_1271
	s_ashr_i32 s59, s20, 6
	s_lshl_b32 s55, s59, 10
	s_mul_i32 s60, s24, 0x680000
	s_add_u32 s60, s70, s60
	s_addc_u32 s61, s71, 0
	s_add_u32 s53, s60, 0x200000
	s_addc_u32 s54, s61, 0
	s_ashr_i32 s39, s38, 31
	s_lshl_b64 s[60:61], s[38:39], 19
	s_add_u32 s46, s53, s60
	s_addc_u32 s47, s54, s61
	s_ashr_i32 s43, s42, 31
	s_lshl_b64 s[60:61], s[42:43], 19
	s_add_u32 s44, s70, 0xab00000
	s_addc_u32 s45, s71, 0
	s_add_u32 s44, s44, s60
	s_addc_u32 s45, s45, s61
	s_add_i32 m0, s55, 0x10000
	s_nop 0
	global_load_lds_dwordx4 v0, s[46:47]
	s_add_i32 m0, s55, 0x12000
	s_nop 0
	global_load_lds_dwordx4 v154, s[46:47]
	s_add_u32 s60, s46, 0x40000
	s_addc_u32 s61, s47, 0
	s_add_i32 m0, s55, 0x14000
	s_nop 0
	global_load_lds_dwordx4 v0, s[60:61]
	s_add_i32 m0, s55, 0x16000
	s_nop 0
	global_load_lds_dwordx4 v154, s[60:61]
	s_mov_b32 m0, s55
	s_nop 0
	global_load_lds_dwordx4 v150, s[44:45]
	s_add_i32 m0, s55, 0x2000
	s_nop 0
	global_load_lds_dwordx4 v152, s[44:45]
	s_add_u32 s60, s44, 0x40000
	s_addc_u32 s61, s45, 0
	s_add_i32 m0, s55, 0x4000
	s_nop 0
	global_load_lds_dwordx4 v150, s[60:61]
	s_add_i32 m0, s55, 0x6000
	s_nop 0
	global_load_lds_dwordx4 v152, s[60:61]
	v_ashrrev_i32_e32 v2, 8, v170
	s_ashr_i32 s95, s94, 31
	v_cmp_gt_i32_e32 vcc, 8, v2
	s_and_saveexec_b64 s[6:7], vcc
	s_cbranch_execz .LBB0_1055
	v_and_b32_e32 v6, 0xff, v170
	v_lshlrev_b32_e32 v3, 2, v6
	v_add_u32_e32 v7, -2, v2
	v_lshl_or_b32 v3, v2, 10, v3
	v_readlane_b32 s8, v254, 19
	v_mul_lo_u32 v2, s90, v2
	v_add_u32_e32 v8, s94, v2
	v_add_u32_e32 v9, s8, v3
	v_mov_b64_e32 v[2:3], s[94:95]
	s_ashr_i32 s91, s90, 31
	v_mad_i64_i32 v[2:3], s[8:9], v7, s90, v[2:3]
	s_lshl_b32 s13, s90, 1
	s_lshl_b64 s[8:9], s[90:91], 1
	s_mov_b64 s[10:11], 0
	s_branch .LBB0_934

.LBB0_1055:
	s_or_b64 exec, exec, s[6:7]
	s_ashr_i32 s9, s20, 6
	s_ashr_i32 s8, s20, 8
	s_lshl_b32 s13, s9, 10
	s_add_u32 s16, s70, 0xab00000
	s_addc_u32 s52, s71, 0
	s_mul_i32 s4, s24, 0x680000
	s_add_u32 s4, s70, s4
	s_addc_u32 s5, s71, 0
	s_add_u32 s53, s4, 0x200000
	s_addc_u32 s54, s5, 0
	s_ashr_i32 s43, s42, 31
	s_ashr_i32 s39, s38, 31
	s_lshl_b64 s[4:5], s[42:43], 19
	s_lshl_b64 s[6:7], s[38:39], 19
	s_add_u32 s46, s53, s6
	s_addc_u32 s47, s54, s7
	s_add_i32 s55, s13, 0
	s_waitcnt vmcnt(0) lgkmcnt(0)
	s_barrier
	s_add_i32 m0, s55, 0x10000
	v_mov_b32_e32 v155, v1
	s_add_i32 m0, s55, 0x12000
	s_add_u32 s6, s46, 0x40000
	s_addc_u32 s7, s47, 0
	s_add_i32 m0, s55, 0x14000
	v_mov_b32_e32 v151, v1
	s_add_i32 m0, s55, 0x16000
	s_add_u32 s44, s16, s4
	s_addc_u32 s45, s52, s5
	s_add_i32 s56, s55, 0x2000
	s_mov_b32 m0, s55
	s_add_u32 s4, s44, 0x40000
	s_mov_b32 m0, s56
	s_addc_u32 s5, s45, 0
	s_add_i32 s57, s55, 0x4000
	s_mov_b32 m0, s57
	s_add_i32 s58, s55, 0x6000
	s_mov_b32 m0, s58
	s_cmp_eq_u32 s8, 1
	v_mov_b32_e32 v153, v1
	s_cselect_b64 s[4:5], -1, 0
	v_lshl_add_u64 v[8:9], s[46:47], 0, v[0:1]
	v_lshl_add_u64 v[6:7], s[46:47], 0, v[154:155]
	v_lshl_add_u64 v[4:5], s[44:45], 0, v[150:151]
	v_lshl_add_u64 v[2:3], s[44:45], 0, v[152:153]
	s_and_b64 vcc, exec, s[4:5]
	s_cbranch_vccz .LBB0_1057
	s_barrier
